# GEMM first-unit prologues: second K-tile staged before the first wait (13 sites), on top of scan preload + bias batching
# speedup vs baseline: 1.0089x; 1.0089x over previous
; #define PG8_STAGE(bufoff, gbase, voff) do { _Pragma("unroll") for (int _i = 0; _i < 2; ++_i) \
;         __builtin_amdgcn_global_load_lds((const unsigned*)((const char*)(gbase) + (voff)[_i]), (PG8_LAS unsigned*)(lds + (bufoff) + ldsw + _i * 8192), 16, 0, 0); } while (0)
; #define PG8_WAIT_V(n) asm volatile("s_waitcnt vmcnt(" #n ")" ::: "memory")
; #define PG8_BAR __builtin_amdgcn_s_barrier()
; template <class Epi, class Sched>
; __device__ __forceinline__ void gemm_phase(PG8_LAS unsigned char* lds, const Gemm g, const Sched& S, const Epi& E) {
;     ...
;     const int aoff = lds_byte(wr * 64 + fr, fq * 8), boff = lds_byte(wc * 32 + fr, fq * 8);
;     ...
;     PG8_STAGE(PG8_SB(0, 0), cB, voffB); PG8_STAGE(PG8_SB(0, 1), cB + hstep, voffB); PG8_STAGE(PG8_SA(0, 0), cA, voffA); PG8_STAGE(PG8_SA(0, 1), cA + hstep, voffA);
;     if (wr == 1) PG8_BAR;
;     PG8_WAIT_V(2); PG8_BAR;
;     PG8_STAGE(PG8_SB(1, 0), cB + kstep, voffB); PG8_STAGE(PG8_SA(1, 0), cA + kstep, voffA); PG8_STAGE(PG8_SB(1, 1), cB + hstep + kstep, voffB);
;     PG8_WAIT_V(6); PG8_BAR;
.LBB0_170:
	s_lshl_b32 s16, s16, 5
	s_and_b32 s22, s16, 0x60
	s_mov_b64 s[16:17], 0x80
	s_add_i32 m0, s3, 0x18000
	v_lshl_add_u64 v[6:7], v[6:7], 0, s[16:17]
	s_lshl_b32 s19, s18, 13
	s_lshl_b32 s23, s22, 7
	global_load_lds_dwordx4 v[6:7], off
	v_lshl_add_u64 v[4:5], v[4:5], 0, s[16:17]
	s_add_i32 m0, s3, 0x1a000
	s_add_i32 s48, s3, 0x8000
	s_add_i32 s49, s3, 0xa000
	global_load_lds_dwordx4 v[4:5], off
	v_lshl_add_u64 v[0:1], v[0:1], 0, s[16:17]
	s_mov_b32 m0, s48
	s_add_u32 s20, s44, 0x80080
	global_load_lds_dwordx4 v[0:1], off
	v_lshl_add_u64 v[0:1], v[2:3], 0, s[16:17]
	s_mov_b32 m0, s49
	s_addc_u32 s21, s45, 0
	global_load_lds_dwordx4 v[0:1], off
	s_add_i32 m0, s3, 0x1c000
	v_lshl_add_u64 v[0:1], s[20:21], 0, v[130:131]
	global_load_lds_dwordx4 v[0:1], off
	v_lshl_add_u64 v[0:1], s[20:21], 0, v[134:135]
	s_add_i32 m0, s3, 0x1e000
	s_cmpk_lt_u32 s5, 0x100
	global_load_lds_dwordx4 v[0:1], off
	s_waitcnt vmcnt(8)
	s_barrier
	v_lshrrev_b32_e32 v1, 1, v8
	v_and_b32_e32 v1, 24, v1
	v_and_b32_e32 v0, 15, v8
	v_lshlrev_b32_e32 v2, 1, v1
	v_lshl_or_b32 v153, s18, 6, v0
	v_lshl_or_b32 v0, v0, 6, v2
	v_lshlrev_b32_e32 v2, 2, v8
	v_and_b32_e32 v2, 32, v2
	v_bitop3_b32 v3, v0, s19, v2 bitop3:0xde
	v_bitop3_b32 v154, v0, s23, v2 bitop3:0xde
	v_lshlrev_b32_e32 v0, 15, v9
	v_and_b32_e32 v0, 0xffff0000, v0
	v_or_b32_e32 v155, s22, v1
	v_lshl_add_u32 v0, v10, 12, v0
	v_and_b32_e32 v1, 1, v9
	v_lshl_or_b32 v0, v1, 6, v0
	v_lshl_add_u32 v136, v11, 1, v0
	v_lshlrev_b32_e32 v0, 15, v12
	v_and_b32_e32 v0, 0xffff0000, v0
	s_waitcnt vmcnt(6)
	v_lshl_add_u32 v0, v13, 12, v0
	v_and_b32_e32 v1, 1, v12
	s_cselect_b64 s[18:19], -1, 0
	v_lshl_or_b32 v0, v1, 6, v0
	s_add_i32 s53, 0, 0x10000
	s_add_i32 s54, 0, 0x14000
	s_sext_i32_i16 s56, s4
	s_ashr_i32 s50, s90, 31
	s_mov_b32 s51, s90
	s_mov_b32 s52, s66
	v_mov_b32_e32 v137, v131
	v_lshl_add_u32 v138, v14, 1, v0
	v_mov_b32_e32 v139, v131
	v_mov_b64_e32 v[140:141], 0x15ab
	v_mov_b64_e32 v[142:143], 0x15aa
	v_add_u32_e32 v156, s53, v154
	v_add_u32_e32 v157, s54, v154
	v_add_u32_e32 v158, 0, v3
	v_mov_b32_e32 v159, 0x358637bd
	s_movk_i32 s55, 0x2b00
	s_barrier
	s_branch .LBB0_173

; #define PG8_STAGE(bufoff, gbase, voff) do { _Pragma("unroll") for (int _i = 0; _i < 2; ++_i) \
;         __builtin_amdgcn_global_load_lds((const unsigned*)((const char*)(gbase) + (voff)[_i]), (PG8_LAS unsigned*)(lds + (bufoff) + ldsw + _i * 8192), 16, 0, 0); } while (0)
; #define PG8_WAIT_V(n) asm volatile("s_waitcnt vmcnt(" #n ")" ::: "memory")
; #define PG8_BAR __builtin_amdgcn_s_barrier()
; template <class Epi, class Sched>
; __device__ __forceinline__ void gemm_phase(PG8_LAS unsigned char* lds, const Gemm g, const Sched& S, const Epi& E) {
;     ...
;     const int aoff = lds_byte(wr * 64 + fr, fq * 8), boff = lds_byte(wc * 32 + fr, fq * 8);
;     ...
;     PG8_STAGE(PG8_SB(0, 0), cB, voffB); PG8_STAGE(PG8_SB(0, 1), cB + hstep, voffB); PG8_STAGE(PG8_SA(0, 0), cA, voffA); PG8_STAGE(PG8_SA(0, 1), cA + hstep, voffA);
;     if (wr == 1) PG8_BAR;
;     PG8_WAIT_V(2); PG8_BAR;
;     PG8_STAGE(PG8_SB(1, 0), cB + kstep, voffB); PG8_STAGE(PG8_SA(1, 0), cA + kstep, voffA); PG8_STAGE(PG8_SB(1, 1), cB + hstep + kstep, voffB);
;     PG8_WAIT_V(6); PG8_BAR;
.LBB0_248:
	s_mov_b64 s[18:19], 0x80
	s_and_b32 s44, s1, 3
	s_add_i32 m0, s3, 0x18000
	v_lshl_add_u64 v[6:7], v[6:7], 0, s[18:19]
	s_lshl_b32 s1, s7, 13
	s_lshl_b32 s20, s44, 12
	global_load_lds_dwordx4 v[6:7], off
	v_lshl_add_u64 v[4:5], v[4:5], 0, s[18:19]
	s_add_i32 m0, s3, 0x1a000
	s_add_i32 s45, s3, 0x8000
	s_add_i32 s46, s3, 0xa000
	global_load_lds_dwordx4 v[4:5], off
	v_lshl_add_u64 v[0:1], v[0:1], 0, s[18:19]
	s_mov_b32 m0, s45
	s_add_u32 s8, s36, 0x158080
	global_load_lds_dwordx4 v[0:1], off
	v_lshl_add_u64 v[0:1], v[2:3], 0, s[18:19]
	s_mov_b32 m0, s46
	s_addc_u32 s9, s37, 0
	global_load_lds_dwordx4 v[0:1], off
	s_add_i32 m0, s3, 0x1c000
	v_lshl_add_u64 v[0:1], s[8:9], 0, v[146:147]
	global_load_lds_dwordx4 v[0:1], off
	v_lshl_add_u64 v[0:1], s[8:9], 0, v[154:155]
	s_add_i32 m0, s3, 0x1e000
	s_cmpk_lt_u32 s6, 0x100
	global_load_lds_dwordx4 v[0:1], off
	s_waitcnt vmcnt(8)
	s_barrier
	v_bfe_u32 v1, v8, 4, 2
	v_and_b32_e32 v0, 15, v8
	v_lshlrev_b32_e32 v2, 4, v1
	v_lshl_or_b32 v153, s7, 6, v0
	v_lshl_or_b32 v0, v0, 6, v2
	v_lshlrev_b32_e32 v2, 2, v8
	v_and_b32_e32 v2, 32, v2
	v_bitop3_b32 v3, v0, s1, v2 bitop3:0xde
	v_bitop3_b32 v172, v0, s20, v2 bitop3:0xde
	v_lshlrev_b32_e32 v0, 2, v1
	v_lshl_or_b32 v173, s44, 5, v0
	v_cmp_eq_u32_e64 s[6:7], 0, v1
	v_lshrrev_b32_e32 v1, 1, v9
	v_mul_lo_u32 v0, v11, s0
	s_mov_b32 s1, 0x15800
	v_mad_u64_u32 v[0:1], s[22:23], v1, s1, v[0:1]
	v_readlane_b32 s68, v247, 38
	v_or_b32_e32 v0, v0, v10
	s_mov_b64 s[8:9], 0x158080
	v_readlane_b32 s69, v247, 39
	v_add_lshl_u32 v0, v0, v12, 1
	v_mov_b32_e32 v1, v147
	v_readlane_b32 s70, v247, 40
	v_readlane_b32 s71, v247, 41
	s_mov_b64 s[52:53], s[68:69]
	v_lshl_add_u64 v[156:157], v[0:1], 0, s[8:9]
	v_lshrrev_b32_e32 v1, 1, v13
	v_mul_lo_u32 v0, v14, s0
	s_cselect_b64 s[20:21], -1, 0
	s_ashr_i32 s47, s90, 31
	s_mov_b64 s[54:55], s[70:71]
	v_mad_u64_u32 v[0:1], s[0:1], v1, s1, v[0:1]
	s_waitcnt vmcnt(6)
	s_add_u32 s50, s54, 0xf0000000
	v_or_b32_e32 v0, v0, v15
	s_addc_u32 s51, s55, -1
	v_add_lshl_u32 v0, v0, v16, 1
	v_mov_b32_e32 v1, v147
	s_add_i32 s52, 0, 0x10000
	s_add_i32 s53, 0, 0x14000
	s_mov_b32 s48, s90
	s_mov_b32 s49, s66
	v_lshl_add_u64 v[158:159], v[0:1], 0, s[8:9]
	v_mov_b64_e32 v[160:161], 0x400
	v_mov_b64_e32 v[162:163], 0x3ff
	v_add_u32_e32 v174, s52, v172
	v_add_u32_e32 v175, s53, v172
	v_add_u32_e32 v176, 0, v3
	v_mbcnt_hi_u32_b32 v177, -1, v149
	s_mov_b32 s54, 0
	s_barrier
	v_readlane_b32 s72, v247, 42
	v_readlane_b32 s73, v247, 43
	v_readlane_b32 s74, v247, 44
	v_readlane_b32 s75, v247, 45
	v_readlane_b32 s76, v247, 46
	v_readlane_b32 s77, v247, 47
	v_readlane_b32 s78, v247, 48
	v_readlane_b32 s79, v247, 49
	v_readlane_b32 s80, v247, 50
	v_readlane_b32 s81, v247, 51
	v_readlane_b32 s82, v247, 52
	v_readlane_b32 s83, v247, 53
	s_branch .LBB0_251

; #define PG8_STAGE(bufoff, gbase, voff) do { _Pragma("unroll") for (int _i = 0; _i < 2; ++_i) \
;         __builtin_amdgcn_global_load_lds((const unsigned*)((const char*)(gbase) + (voff)[_i]), (PG8_LAS unsigned*)(lds + (bufoff) + ldsw + _i * 8192), 16, 0, 0); } while (0)
; #define PG8_WAIT_V(n) asm volatile("s_waitcnt vmcnt(" #n ")" ::: "memory")
; #define PG8_BAR __builtin_amdgcn_s_barrier()
; template <class Epi, class Sched>
; __device__ __forceinline__ void gemm_phase(PG8_LAS unsigned char* lds, const Gemm g, const Sched& S, const Epi& E) {
;     ...
;     const int aoff = lds_byte(wr * 64 + fr, fq * 8), boff = lds_byte(wc * 32 + fr, fq * 8);
;     ...
;     PG8_STAGE(PG8_SB(0, 0), cB, voffB); PG8_STAGE(PG8_SB(0, 1), cB + hstep, voffB); PG8_STAGE(PG8_SA(0, 0), cA, voffA); PG8_STAGE(PG8_SA(0, 1), cA + hstep, voffA);
;     if (wr == 1) PG8_BAR;
;     PG8_WAIT_V(2); PG8_BAR;
;     PG8_STAGE(PG8_SB(1, 0), cB + kstep, voffB); PG8_STAGE(PG8_SA(1, 0), cA + kstep, voffA); PG8_STAGE(PG8_SB(1, 1), cB + hstep + kstep, voffB);
;     PG8_WAIT_V(6); PG8_BAR;
.LBB0_288:
	s_cmpk_gt_i32 s66, 0x9f
	s_cselect_b32 s55, 6, 4
	s_lshl_b32 s22, s8, 6
	s_lshl_b32 s20, s8, 13
	s_lshl_b32 s4, s4, 5
	s_mov_b64 s[8:9], 0x80
	s_and_b32 s4, s4, 0x60
	s_add_i32 m0, s3, 0x18000
	v_lshl_add_u64 v[6:7], v[6:7], 0, s[8:9]
	s_lshl_b32 s21, s4, 7
	global_load_lds_dwordx4 v[6:7], off
	v_lshl_add_u64 v[4:5], v[4:5], 0, s[8:9]
	s_add_i32 m0, s3, 0x1a000
	s_add_i32 s47, s3, 0x8000
	s_add_i32 s49, s3, 0xa000
	global_load_lds_dwordx4 v[4:5], off
	v_lshl_add_u64 v[0:1], v[0:1], 0, s[8:9]
	s_mov_b32 m0, s47
	s_add_u32 s18, s38, 0x158080
	global_load_lds_dwordx4 v[0:1], off
	v_lshl_add_u64 v[0:1], v[2:3], 0, s[8:9]
	s_mov_b32 m0, s49
	s_addc_u32 s19, s39, 0
	global_load_lds_dwordx4 v[0:1], off
	s_add_i32 m0, s3, 0x1c000
	v_lshl_add_u64 v[0:1], s[18:19], 0, v[130:131]
	global_load_lds_dwordx4 v[0:1], off
	v_lshl_add_u64 v[0:1], s[18:19], 0, v[128:129]
	s_add_i32 m0, s3, 0x1e000
	v_bfe_u32 v2, v11, 4, 2
	global_load_lds_dwordx4 v[0:1], off
	s_waitcnt vmcnt(8)
	s_barrier
	v_and_b32_e32 v0, 15, v11
	v_lshlrev_b32_e32 v1, 4, v2
	v_lshlrev_b32_e32 v3, 2, v11
	s_cmpk_lt_u32 s0, 0x100
	v_lshl_or_b32 v1, v0, 6, v1
	v_and_b32_e32 v3, 32, v3
	s_cselect_b64 s[18:19], -1, 0
	s_ashr_i32 s0, s22, 31
	v_bitop3_b32 v4, v1, s20, v3 bitop3:0xde
	v_bitop3_b32 v140, v1, s21, v3 bitop3:0xde
	v_or_b32_e32 v0, s22, v0
	v_mov_b32_e32 v1, s0
	v_readlane_b32 s22, v246, 29
	v_lshlrev_b64 v[0:1], 13, v[0:1]
	v_readlane_b32 s23, v246, 30
	s_mov_b32 s0, 0x15800
	s_mov_b64 s[20:21], 0x158080
	v_lshl_add_u64 v[134:135], s[22:23], 0, v[0:1]
	v_lshrrev_b32_e32 v1, 1, v14
	v_mul_lo_u32 v0, v13, s1
	v_mad_u64_u32 v[0:1], s[22:23], v1, s0, v[0:1]
	v_or_b32_e32 v0, v0, v15
	v_add_lshl_u32 v132, v0, v16, 1
	v_lshrrev_b32_e32 v1, 1, v8
	v_mul_lo_u32 v0, v9, s1
	v_mad_u64_u32 v[0:1], s[0:1], v1, s0, v[0:1]
	s_waitcnt vmcnt(6)
	v_or_b32_e32 v0, v0, v10
	v_lshlrev_b32_e32 v2, 2, v2
	v_lshl_add_u64 v[136:137], v[132:133], 0, s[20:21]
	v_add_lshl_u32 v132, v0, v12, 1
	s_add_i32 s50, 0, 0x10000
	s_add_i32 s51, 0, 0x14000
	v_lshl_add_u64 v[138:139], v[132:133], 0, s[20:21]
	v_add_u32_e32 v141, s50, v140
	v_add_u32_e32 v142, s51, v140
	v_add_u32_e32 v143, 0, v4
	s_lshl_b32 s4, s4, 2
	v_lshlrev_b32_e32 v132, 2, v2
	s_mov_b32 s52, s5
	s_barrier
	s_branch .LBB0_291

; #define PG8_STAGE(bufoff, gbase, voff) do { _Pragma("unroll") for (int _i = 0; _i < 2; ++_i) \
;         __builtin_amdgcn_global_load_lds((const unsigned*)((const char*)(gbase) + (voff)[_i]), (PG8_LAS unsigned*)(lds + (bufoff) + ldsw + _i * 8192), 16, 0, 0); } while (0)
; #define PG8_WAIT_V(n) asm volatile("s_waitcnt vmcnt(" #n ")" ::: "memory")
; #define PG8_BAR __builtin_amdgcn_s_barrier()
; template <class Epi, class Sched>
; __device__ __forceinline__ void gemm_phase(PG8_LAS unsigned char* lds, const Gemm g, const Sched& S, const Epi& E) {
;     ...
;     const int aoff = lds_byte(wr * 64 + fr, fq * 8), boff = lds_byte(wc * 32 + fr, fq * 8);
;     ...
;     PG8_STAGE(PG8_SB(0, 0), cB, voffB); PG8_STAGE(PG8_SB(0, 1), cB + hstep, voffB); PG8_STAGE(PG8_SA(0, 0), cA, voffA); PG8_STAGE(PG8_SA(0, 1), cA + hstep, voffA);
;     if (wr == 1) PG8_BAR;
;     PG8_WAIT_V(2); PG8_BAR;
;     PG8_STAGE(PG8_SB(1, 0), cB + kstep, voffB); PG8_STAGE(PG8_SA(1, 0), cA + kstep, voffA); PG8_STAGE(PG8_SB(1, 1), cB + hstep + kstep, voffB);
;     PG8_WAIT_V(6); PG8_BAR;
.LBB0_426:
	v_lshrrev_b32_e32 v15, 1, v8
	v_and_b32_e32 v15, 24, v15
	v_and_b32_e32 v153, 15, v8
	v_lshlrev_b32_e32 v16, 1, v15
	v_lshlrev_b32_e32 v17, 2, v8
	v_lshl_or_b32 v16, v153, 6, v16
	s_lshl_b32 s1, s6, 13
	v_and_b32_e32 v17, 32, v17
	v_bitop3_b32 v18, v16, s1, v17 bitop3:0xde
	s_lshl_b32 s1, s7, 5
	s_and_b32 s1, s1, 0x60
	s_lshl_b32 s47, s6, 6
	s_lshl_b32 s6, s1, 7
	v_bitop3_b32 v155, v16, s6, v17 bitop3:0xde
	s_mov_b64 s[6:7], 0x80
	s_add_i32 m0, s40, 0x18000
	v_lshl_add_u64 v[6:7], v[6:7], 0, s[6:7]
	global_load_lds_dwordx4 v[6:7], off
	v_lshl_add_u64 v[4:5], v[4:5], 0, s[6:7]
	s_add_i32 m0, s40, 0x1a000
	s_add_i32 s48, s40, 0x8000
	s_add_i32 s49, s40, 0xa000
	global_load_lds_dwordx4 v[4:5], off
	v_lshl_add_u64 v[0:1], v[0:1], 0, s[6:7]
	s_mov_b32 m0, s48
	s_add_u32 s10, s38, 0x80080
	global_load_lds_dwordx4 v[0:1], off
	v_lshl_add_u64 v[0:1], v[2:3], 0, s[6:7]
	s_mov_b32 m0, s49
	s_addc_u32 s11, s39, 0
	global_load_lds_dwordx4 v[0:1], off
	s_add_i32 m0, s40, 0x1c000
	v_lshl_add_u64 v[0:1], s[10:11], 0, v[130:131]
	global_load_lds_dwordx4 v[0:1], off
	v_lshl_add_u64 v[0:1], s[10:11], 0, v[134:135]
	s_add_i32 m0, s40, 0x1e000
	s_cmpk_lt_u32 s8, 0x100
	global_load_lds_dwordx4 v[0:1], off
	s_waitcnt vmcnt(8)
	s_barrier
	v_readlane_b32 s8, v246, 39
	v_lshlrev_b32_e32 v0, 5, v153
	v_mov_b32_e32 v1, v131
	v_readlane_b32 s9, v246, 40
	v_and_b32_e32 v2, 16, v8
	v_mov_b32_e32 v3, v131
	v_lshl_add_u64 v[0:1], s[8:9], 0, v[0:1]
	v_lshl_add_u64 v[136:137], v[0:1], 0, v[2:3]
	v_lshlrev_b32_e32 v0, 15, v9
	v_and_b32_e32 v0, 0xffff0000, v0
	v_lshl_add_u32 v0, v10, 12, v0
	v_and_b32_e32 v1, 1, v9
	v_lshl_or_b32 v0, v1, 6, v0
	v_lshl_add_u32 v138, v11, 1, v0
	v_lshlrev_b32_e32 v0, 15, v12
	v_and_b32_e32 v0, 0xffff0000, v0
	s_waitcnt vmcnt(6)
	v_lshl_add_u32 v0, v13, 12, v0
	v_and_b32_e32 v1, 1, v12
	s_cselect_b64 s[10:11], -1, 0
	v_lshl_or_b32 v0, v1, 6, v0
	s_add_i32 s53, 0, 0x10000
	s_add_i32 s54, 0, 0x14000
	s_ashr_i32 s50, s90, 31
	s_mov_b32 s51, s90
	s_mov_b32 s52, s66
	v_or_b32_e32 v157, s1, v15
	v_mov_b32_e32 v139, v131
	v_lshl_add_u32 v140, v14, 1, v0
	v_mov_b32_e32 v141, v131
	v_mov_b64_e32 v[142:143], 0x800
	v_mov_b64_e32 v[146:147], 0x7ff
	v_add_u32_e32 v164, s53, v155
	v_add_u32_e32 v165, s54, v155
	v_add_u32_e32 v166, 0, v18
	v_mov_b32_e32 v167, 0x358637bd
	s_movk_i32 s55, 0xbff
	s_movk_i32 s56, 0x300
	v_mov_b32_e32 v168, 0x7ffa0000
	s_barrier
	s_branch .LBB0_429

; #define PG8_STAGE(bufoff, gbase, voff) do { _Pragma("unroll") for (int _i = 0; _i < 2; ++_i) \
;         __builtin_amdgcn_global_load_lds((const unsigned*)((const char*)(gbase) + (voff)[_i]), (PG8_LAS unsigned*)(lds + (bufoff) + ldsw + _i * 8192), 16, 0, 0); } while (0)
; #define PG8_WAIT_V(n) asm volatile("s_waitcnt vmcnt(" #n ")" ::: "memory")
; #define PG8_BAR __builtin_amdgcn_s_barrier()
; template <class Epi, class Sched>
; __device__ __forceinline__ void gemm_phase(PG8_LAS unsigned char* lds, const Gemm g, const Sched& S, const Epi& E) {
;     ...
;     const int aoff = lds_byte(wr * 64 + fr, fq * 8), boff = lds_byte(wc * 32 + fr, fq * 8);
;     ...
;     PG8_STAGE(PG8_SB(0, 0), cB, voffB); PG8_STAGE(PG8_SB(0, 1), cB + hstep, voffB); PG8_STAGE(PG8_SA(0, 0), cA, voffA); PG8_STAGE(PG8_SA(0, 1), cA + hstep, voffA);
;     if (wr == 1) PG8_BAR;
;     PG8_WAIT_V(2); PG8_BAR;
;     PG8_STAGE(PG8_SB(1, 0), cB + kstep, voffB); PG8_STAGE(PG8_SA(1, 0), cA + kstep, voffA); PG8_STAGE(PG8_SB(1, 1), cB + hstep + kstep, voffB);
;     PG8_WAIT_V(6); PG8_BAR;
.LBB0_510:
	v_bfe_u32 v10, v8, 4, 2
	v_and_b32_e32 v9, 15, v8
	v_lshlrev_b32_e32 v11, 4, v10
	v_lshlrev_b32_e32 v8, 2, v8
	s_lshl_b32 s1, s1, 5
	s_mov_b64 s[14:15], 0x80
	s_lshl_b32 s22, s4, 6
	v_lshl_or_b32 v11, v9, 6, v11
	s_lshl_b32 s4, s4, 13
	v_and_b32_e32 v8, 32, v8
	s_and_b32 s1, s1, 0x60
	s_add_i32 m0, s9, 0x18000
	v_lshl_add_u64 v[6:7], v[6:7], 0, s[14:15]
	v_bitop3_b32 v12, v11, s4, v8 bitop3:0xde
	s_lshl_b32 s4, s1, 7
	global_load_lds_dwordx4 v[6:7], off
	v_lshl_add_u64 v[4:5], v[4:5], 0, s[14:15]
	s_add_i32 m0, s9, 0x1a000
	s_add_i32 s56, s9, 0x8000
	s_add_i32 s57, s9, 0xa000
	global_load_lds_dwordx4 v[4:5], off
	v_lshl_add_u64 v[0:1], v[0:1], 0, s[14:15]
	s_mov_b32 m0, s56
	s_add_u32 s20, s16, 0x80080
	global_load_lds_dwordx4 v[0:1], off
	v_lshl_add_u64 v[0:1], v[2:3], 0, s[14:15]
	s_mov_b32 m0, s57
	s_addc_u32 s21, s17, 0
	global_load_lds_dwordx4 v[0:1], off
	s_add_i32 m0, s9, 0x1c000
	v_lshl_add_u64 v[0:1], s[20:21], 0, v[130:131]
	global_load_lds_dwordx4 v[0:1], off
	v_lshl_add_u64 v[0:1], s[20:21], 0, v[128:129]
	s_add_i32 m0, s9, 0x1e000
	s_cmpk_lt_u32 s0, 0x100
	global_load_lds_dwordx4 v[0:1], off
	s_waitcnt vmcnt(8)
	s_barrier
	s_cselect_b64 s[20:21], -1, 0
	s_ashr_i32 s0, s22, 31
	v_bitop3_b32 v8, v11, s4, v8 bitop3:0xde
	s_waitcnt vmcnt(6)
	v_or_b32_e32 v0, s22, v9
	v_mov_b32_e32 v1, s0
	v_readlane_b32 s22, v246, 29
	s_add_i32 s60, 0, 0x10000
	s_add_i32 s62, 0, 0x14000
	v_lshlrev_b32_e32 v2, 2, v10
	v_lshlrev_b64 v[0:1], 14, v[0:1]
	v_readlane_b32 s23, v246, 30
	v_add_u32_e32 v136, s60, v8
	v_add_u32_e32 v137, s62, v8
	s_add_i32 s60, s60, s33
	s_add_i32 s62, s62, s33
	s_add_i32 s64, 0, 0x18000
	s_add_i32 s65, 0, 0x1c000
	v_lshl_add_u64 v[134:135], s[22:23], 0, v[0:1]
	v_add_u32_e32 v138, 0, v12
	s_lshl_b32 s4, s1, 2
	v_lshlrev_b32_e32 v132, 2, v2
	s_add_i32 s58, s9, 0xc000
	s_add_i32 s59, s9, 0xe000
	s_add_i32 s61, s60, 0x2000
	s_add_i32 s63, s62, 0x2000
	v_add_u32_e32 v139, s64, v8
	v_add_u32_e32 v140, s65, v8
	s_mov_b32 s66, s5
	s_barrier
	s_branch .LBB0_513

; #define PG8_STAGE(bufoff, gbase, voff) do { _Pragma("unroll") for (int _i = 0; _i < 2; ++_i) \
;         __builtin_amdgcn_global_load_lds((const unsigned*)((const char*)(gbase) + (voff)[_i]), (PG8_LAS unsigned*)(lds + (bufoff) + ldsw + _i * 8192), 16, 0, 0); } while (0)
; #define PG8_WAIT_V(n) asm volatile("s_waitcnt vmcnt(" #n ")" ::: "memory")
; #define PG8_BAR __builtin_amdgcn_s_barrier()
; template <class Epi, class Sched>
; __device__ __forceinline__ void gemm_phase(PG8_LAS unsigned char* lds, const Gemm g, const Sched& S, const Epi& E) {
;     ...
;     const int aoff = lds_byte(wr * 64 + fr, fq * 8), boff = lds_byte(wc * 32 + fr, fq * 8);
;     ...
;     PG8_STAGE(PG8_SB(0, 0), cB, voffB); PG8_STAGE(PG8_SB(0, 1), cB + hstep, voffB); PG8_STAGE(PG8_SA(0, 0), cA, voffA); PG8_STAGE(PG8_SA(0, 1), cA + hstep, voffA);
;     if (wr == 1) PG8_BAR;
;     PG8_WAIT_V(2); PG8_BAR;
;     PG8_STAGE(PG8_SB(1, 0), cB + kstep, voffB); PG8_STAGE(PG8_SA(1, 0), cA + kstep, voffA); PG8_STAGE(PG8_SB(1, 1), cB + hstep + kstep, voffB);
;     PG8_WAIT_V(6); PG8_BAR;
.LBB0_669:
	s_lshl_b32 s6, s6, 5
	s_lshl_b32 s14, s7, 6
	s_lshl_b32 s15, s7, 13
	s_and_b32 s16, s6, 0x60
	s_mov_b64 s[6:7], 0x80
	s_add_i32 m0, s2, 0x18000
	v_lshl_add_u64 v[6:7], v[6:7], 0, s[6:7]
	s_lshl_b32 s17, s16, 7
	global_load_lds_dwordx4 v[6:7], off
	v_lshl_add_u64 v[4:5], v[4:5], 0, s[6:7]
	s_add_i32 m0, s2, 0x1a000
	s_add_i32 s48, s2, 0x8000
	s_add_i32 s49, s2, 0xa000
	global_load_lds_dwordx4 v[4:5], off
	v_lshl_add_u64 v[0:1], v[0:1], 0, s[6:7]
	s_mov_b32 m0, s48
	s_add_u32 s10, s8, 0x18080
	global_load_lds_dwordx4 v[0:1], off
	v_lshl_add_u64 v[0:1], v[2:3], 0, s[6:7]
	s_mov_b32 m0, s49
	s_addc_u32 s11, s9, 0
	s_add_i32 s50, s2, 0x1c000
	global_load_lds_dwordx4 v[0:1], off
	v_lshl_add_u64 v[0:1], s[10:11], 0, v[66:67]
	s_mov_b32 m0, s50
	s_add_i32 s51, s2, 0x1e000
	global_load_lds_dwordx4 v[0:1], off
	v_lshl_add_u64 v[0:1], s[10:11], 0, v[64:65]
	s_mov_b32 m0, s51
	v_lshlrev_b32_e32 v3, 2, v8
	global_load_lds_dwordx4 v[0:1], off
	s_waitcnt vmcnt(8)
	s_barrier
	v_and_b32_e32 v1, 15, v8
	v_and_b32_e32 v0, 48, v8
	s_cmpk_lt_u32 s1, 0x100
	v_lshl_or_b32 v2, v1, 6, v0
	v_and_b32_e32 v3, 32, v3
	s_cselect_b64 s[10:11], -1, 0
	s_ashr_i32 s1, s14, 31
	v_bitop3_b32 v4, v2, s15, v3 bitop3:0xde
	v_bitop3_b32 v5, v2, s17, v3 bitop3:0xde
	v_or_b32_e32 v2, s14, v1
	v_mov_b32_e32 v3, s1
	s_lshl_b32 s1, s16, 2
	v_readlane_b32 s14, v246, 15
	v_readlane_b32 s15, v246, 16
	s_add_u32 s14, s14, s1
	s_addc_u32 s15, s15, 0
	s_add_i32 s1, 0, 0x10000
	s_waitcnt vmcnt(6)
	v_mov_b32_e32 v1, v67
	s_add_i32 s54, s1, s0
	v_add_u32_e32 v70, s1, v5
	s_add_i32 s1, 0, 0x18000
	v_lshl_add_u64 v[0:1], s[14:15], 0, v[0:1]
	v_lshlrev_b64 v[2:3], 9, v[2:3]
	s_add_i32 s56, s1, s0
	v_lshl_add_u64 v[68:69], v[0:1], 0, v[2:3]
	s_add_i32 s52, s2, 0xc000
	s_add_i32 s53, s2, 0xe000
	v_add_u32_e32 v71, 0, v4
	s_add_i32 s55, s54, 0x2000
	s_add_i32 s57, s56, 0x2000
	v_add_u32_e32 v72, s1, v5
	s_mov_b32 s18, s66
	s_mov_b64 s[14:15], s[12:13]
	s_barrier
	s_branch .LBB0_672

; #define PG8_STAGE(bufoff, gbase, voff) do { _Pragma("unroll") for (int _i = 0; _i < 2; ++_i) \
;         __builtin_amdgcn_global_load_lds((const unsigned*)((const char*)(gbase) + (voff)[_i]), (PG8_LAS unsigned*)(lds + (bufoff) + ldsw + _i * 8192), 16, 0, 0); } while (0)
; #define PG8_WAIT_V(n) asm volatile("s_waitcnt vmcnt(" #n ")" ::: "memory")
; #define PG8_BAR __builtin_amdgcn_s_barrier()
; template <class Epi, class Sched>
; __device__ __forceinline__ void gemm_phase(PG8_LAS unsigned char* lds, const Gemm g, const Sched& S, const Epi& E) {
;     ...
;     const int aoff = lds_byte(wr * 64 + fr, fq * 8), boff = lds_byte(wc * 32 + fr, fq * 8);
;     ...
;     PG8_STAGE(PG8_SB(0, 0), cB, voffB); PG8_STAGE(PG8_SB(0, 1), cB + hstep, voffB); PG8_STAGE(PG8_SA(0, 0), cA, voffA); PG8_STAGE(PG8_SA(0, 1), cA + hstep, voffA);
;     if (wr == 1) PG8_BAR;
;     PG8_WAIT_V(2); PG8_BAR;
;     PG8_STAGE(PG8_SB(1, 0), cB + kstep, voffB); PG8_STAGE(PG8_SA(1, 0), cA + kstep, voffA); PG8_STAGE(PG8_SB(1, 1), cB + hstep + kstep, voffB);
;     PG8_WAIT_V(6); PG8_BAR;
.LBB0_884:
	s_lshl_b32 s6, s6, 5
	s_and_b32 s15, s6, 0x60
	s_mov_b64 s[6:7], 0x80
	s_add_i32 m0, s33, 0x18000
	v_lshl_add_u64 v[6:7], v[6:7], 0, s[6:7]
	s_lshl_b32 s14, s9, 13
	s_lshl_b32 s22, s15, 7
	global_load_lds_dwordx4 v[6:7], off
	v_lshl_add_u64 v[4:5], v[4:5], 0, s[6:7]
	s_add_i32 m0, s33, 0x1a000
	s_add_i32 s40, s33, 0x8000
	s_add_i32 s41, s33, 0xa000
	global_load_lds_dwordx4 v[4:5], off
	v_lshl_add_u64 v[0:1], v[0:1], 0, s[6:7]
	s_mov_b32 m0, s40
	s_add_u32 s12, s18, 0x18080
	global_load_lds_dwordx4 v[0:1], off
	v_lshl_add_u64 v[0:1], v[2:3], 0, s[6:7]
	s_mov_b32 m0, s41
	s_addc_u32 s13, s19, 0
	global_load_lds_dwordx4 v[0:1], off
	s_add_i32 m0, s33, 0x1c000
	v_lshl_add_u64 v[0:1], s[12:13], 0, v[132:133]
	global_load_lds_dwordx4 v[0:1], off
	v_lshl_add_u64 v[0:1], s[12:13], 0, v[128:129]
	s_add_i32 m0, s33, 0x1e000
	s_cmpk_lt_u32 s8, 0x100
	global_load_lds_dwordx4 v[0:1], off
	s_waitcnt vmcnt(8)
	s_barrier
	v_lshrrev_b32_e32 v1, 1, v9
	v_and_b32_e32 v2, 24, v1
	v_and_b32_e32 v0, 15, v9
	v_lshlrev_b32_e32 v3, 1, v2
	v_lshl_or_b32 v142, s9, 6, v0
	v_lshl_or_b32 v0, v0, 6, v3
	v_lshlrev_b32_e32 v3, 2, v9
	v_and_b32_e32 v3, 32, v3
	v_bitop3_b32 v4, v0, s14, v3 bitop3:0xde
	v_bitop3_b32 v5, v0, s22, v3 bitop3:0xde
	v_and_b32_e32 v0, 8, v1
	v_or_b32_e32 v1, s15, v2
	v_lshrrev_b32_e32 v143, 4, v1
	v_lshrrev_b32_e32 v1, 1, v14
	v_mul_lo_u32 v2, v13, s11
	s_movk_i32 s22, 0x1800
	v_mad_u64_u32 v[2:3], s[14:15], v1, s22, v[2:3]
	v_or_b32_e32 v1, v2, v15
	v_add_lshl_u32 v136, v1, v16, 1
	v_lshrrev_b32_e32 v1, 1, v8
	v_mul_lo_u32 v2, v10, s11
	v_mad_u64_u32 v[2:3], s[14:15], v1, s22, v[2:3]
	s_mov_b64 s[12:13], 0x18080
	s_waitcnt vmcnt(6)
	s_cselect_b64 s[8:9], -1, 0
	v_or_b32_e32 v1, v2, v11
	s_add_i32 s44, 0, 0x10000
	s_add_i32 s46, 0, 0x14000
	s_add_i32 s48, 0, 0x18000
	s_add_i32 s50, 0, 0x1c000
	v_lshl_add_u64 v[138:139], v[136:137], 0, s[12:13]
	v_add_lshl_u32 v136, v1, v12, 1
	v_add_u32_e32 v145, s44, v5
	v_add_u32_e32 v146, s46, v5
	s_add_i32 s44, s44, s10
	s_add_i32 s46, s46, s10
	v_add_u32_e32 v151, s48, v5
	v_add_u32_e32 v153, s50, v5
	s_add_i32 s48, s48, s10
	s_add_i32 s50, s50, s10
	v_or_b32_e32 v144, 8, v143
	v_lshl_add_u64 v[140:141], v[136:137], 0, s[12:13]
	v_add_u32_e32 v147, 0, v4
	s_add_i32 s42, s33, 0xc000
	s_add_i32 s43, s33, 0xe000
	s_add_i32 s45, s44, 0x2000
	s_add_i32 s47, s46, 0x2000
	v_lshlrev_b32_e32 v136, 1, v0
	s_add_i32 s49, s48, 0x2000
	s_add_i32 s51, s50, 0x2000
	s_mov_b32 s55, s66
	s_mov_b64 s[10:11], s[16:17]
	s_barrier
	s_branch .LBB0_887

; #define PG8_STAGE(bufoff, gbase, voff) do { _Pragma("unroll") for (int _i = 0; _i < 2; ++_i) \
;         __builtin_amdgcn_global_load_lds((const unsigned*)((const char*)(gbase) + (voff)[_i]), (PG8_LAS unsigned*)(lds + (bufoff) + ldsw + _i * 8192), 16, 0, 0); } while (0)
; #define PG8_WAIT_V(n) asm volatile("s_waitcnt vmcnt(" #n ")" ::: "memory")
; #define PG8_BAR __builtin_amdgcn_s_barrier()
; template <class Epi, class Sched>
; __device__ __forceinline__ void gemm_phase(PG8_LAS unsigned char* lds, const Gemm g, const Sched& S, const Epi& E) {
;     ...
;     const int aoff = lds_byte(wr * 64 + fr, fq * 8), boff = lds_byte(wc * 32 + fr, fq * 8);
;     ...
;     PG8_STAGE(PG8_SB(0, 0), cB, voffB); PG8_STAGE(PG8_SB(0, 1), cB + hstep, voffB); PG8_STAGE(PG8_SA(0, 0), cA, voffA); PG8_STAGE(PG8_SA(0, 1), cA + hstep, voffA);
;     if (wr == 1) PG8_BAR;
;     PG8_WAIT_V(2); PG8_BAR;
;     PG8_STAGE(PG8_SB(1, 0), cB + kstep, voffB); PG8_STAGE(PG8_SA(1, 0), cA + kstep, voffA); PG8_STAGE(PG8_SB(1, 1), cB + hstep + kstep, voffB);
;     PG8_WAIT_V(6); PG8_BAR;
.LBB0_956:
	s_and_b32 s41, s8, 3
	s_mov_b64 s[8:9], 0x80
	s_add_i32 m0, s3, 0x18000
	v_lshl_add_u64 v[6:7], v[6:7], 0, s[8:9]
	s_lshl_b32 s14, s11, 13
	s_lshl_b32 s15, s41, 12
	global_load_lds_dwordx4 v[6:7], off
	v_lshl_add_u64 v[4:5], v[4:5], 0, s[8:9]
	s_add_i32 m0, s3, 0x1a000
	s_add_i32 s50, s3, 0x8000
	s_add_i32 s51, s3, 0xa000
	global_load_lds_dwordx4 v[4:5], off
	v_lshl_add_u64 v[0:1], v[0:1], 0, s[8:9]
	s_mov_b32 m0, s50
	s_add_u32 s12, s46, 0x40080
	global_load_lds_dwordx4 v[0:1], off
	v_lshl_add_u64 v[0:1], v[2:3], 0, s[8:9]
	s_mov_b32 m0, s51
	s_addc_u32 s13, s47, 0
	global_load_lds_dwordx4 v[0:1], off
	s_add_i32 m0, s3, 0x1c000
	v_lshl_add_u64 v[0:1], s[12:13], 0, v[146:147]
	global_load_lds_dwordx4 v[0:1], off
	v_lshl_add_u64 v[0:1], s[12:13], 0, v[160:161]
	s_add_i32 m0, s3, 0x1e000
	s_cmpk_lt_u32 s10, 0x100
	global_load_lds_dwordx4 v[0:1], off
	s_waitcnt vmcnt(8)
	s_barrier
	v_bfe_u32 v1, v8, 4, 2
	v_and_b32_e32 v0, 15, v8
	v_lshlrev_b32_e32 v3, 4, v1
	v_lshl_or_b32 v151, s11, 6, v0
	v_lshl_or_b32 v0, v0, 6, v3
	v_lshlrev_b32_e32 v3, 2, v8
	v_and_b32_e32 v3, 32, v3
	v_bitop3_b32 v4, v0, s14, v3 bitop3:0xde
	v_bitop3_b32 v153, v0, s15, v3 bitop3:0xde
	v_lshlrev_b32_e32 v0, 14, v9
	v_and_b32_e32 v0, 0xffff8000, v0
	v_lshlrev_b32_e32 v2, 3, v1
	v_cmp_ne_u32_e64 s[12:13], 0, v1
	v_lshl_add_u32 v0, v10, 11, v0
	v_and_b32_e32 v1, 1, v9
	v_lshl_or_b32 v0, v1, 6, v0
	v_lshl_add_u32 v162, v11, 1, v0
	v_lshlrev_b32_e32 v0, 14, v12
	s_cselect_b64 s[10:11], -1, 0
	s_ashr_i32 s52, s90, 31
	v_readlane_b32 s16, v247, 63
	v_and_b32_e32 v0, 0xffff8000, v0
	s_waitcnt vmcnt(6)
	v_readlane_b32 s17, v246, 0
	s_add_u32 s16, s16, 0x1000
	v_lshl_add_u32 v0, v13, 11, v0
	v_and_b32_e32 v1, 1, v12
	v_readlane_b32 s18, v246, 1
	v_readlane_b32 s20, v246, 3
	v_readlane_b32 s21, v246, 4
	v_readlane_b32 s24, v246, 7
	v_readlane_b32 s25, v246, 8
	s_addc_u32 s17, s17, 0
	v_lshl_or_b32 v0, v1, 6, v0
	s_add_i32 s55, 0, 0x10000
	s_add_i32 s60, 0, 0x14000
	v_lshl_or_b32 v155, s41, 5, v2
	s_mov_b32 s53, s90
	v_readlane_b32 s54, v247, 54
	v_readlane_b32 s22, v246, 5
	v_mov_b32_e32 v163, v147
	v_lshl_add_u32 v164, v14, 1, v0
	v_mov_b32_e32 v165, v147
	v_mov_b64_e32 v[166:167], 0x408
	v_mov_b64_e32 v[168:169], 0x407
	v_add_u32_e32 v157, s55, v153
	v_add_u32_e32 v172, s60, v153
	v_add_u32_e32 v173, 0, v4
	s_mov_b32 s18, 0xbfb8aa3b
	s_mov_b32 s61, 0
	s_mov_b64 s[20:21], s[36:37]
	s_mov_b64 s[24:25], s[38:39]
	s_barrier
	v_readlane_b32 s19, v246, 2
	v_readlane_b32 s23, v246, 6
	v_readlane_b32 s26, v246, 9
	v_readlane_b32 s27, v246, 10
	v_readlane_b32 s28, v246, 11
	v_readlane_b32 s29, v246, 12
	v_readlane_b32 s30, v246, 13
	v_readlane_b32 s31, v246, 14
	s_branch .LBB0_959

; #define PG8_STAGE(bufoff, gbase, voff) do { _Pragma("unroll") for (int _i = 0; _i < 2; ++_i) \
;         __builtin_amdgcn_global_load_lds((const unsigned*)((const char*)(gbase) + (voff)[_i]), (PG8_LAS unsigned*)(lds + (bufoff) + ldsw + _i * 8192), 16, 0, 0); } while (0)
; #define PG8_WAIT_V(n) asm volatile("s_waitcnt vmcnt(" #n ")" ::: "memory")
; #define PG8_BAR __builtin_amdgcn_s_barrier()
; template <class Epi, class Sched>
; __device__ __forceinline__ void gemm_phase(PG8_LAS unsigned char* lds, const Gemm g, const Sched& S, const Epi& E) {
;     ...
;     const int aoff = lds_byte(wr * 64 + fr, fq * 8), boff = lds_byte(wc * 32 + fr, fq * 8);
;     ...
;     PG8_STAGE(PG8_SB(0, 0), cB, voffB); PG8_STAGE(PG8_SB(0, 1), cB + hstep, voffB); PG8_STAGE(PG8_SA(0, 0), cA, voffA); PG8_STAGE(PG8_SA(0, 1), cA + hstep, voffA);
;     if (wr == 1) PG8_BAR;
;     PG8_WAIT_V(2); PG8_BAR;
;     PG8_STAGE(PG8_SB(1, 0), cB + kstep, voffB); PG8_STAGE(PG8_SA(1, 0), cA + kstep, voffA); PG8_STAGE(PG8_SB(1, 1), cB + hstep + kstep, voffB);
;     PG8_WAIT_V(6); PG8_BAR;
.LBB0_1064:
	s_mov_b64 s[10:11], 0x80
	s_and_b32 s41, s1, 3
	s_add_i32 m0, s3, 0x18000
	v_lshl_add_u64 v[8:9], v[8:9], 0, s[10:11]
	s_lshl_b32 s1, s0, 13
	s_lshl_b32 s15, s41, 12
	global_load_lds_dwordx4 v[8:9], off
	v_lshl_add_u64 v[6:7], v[6:7], 0, s[10:11]
	s_add_i32 m0, s3, 0x1a000
	s_add_i32 s50, s3, 0x8000
	s_add_i32 s51, s3, 0xa000
	global_load_lds_dwordx4 v[6:7], off
	v_lshl_add_u64 v[2:3], v[2:3], 0, s[10:11]
	s_mov_b32 m0, s50
	s_add_u32 s16, s44, 0x80080
	global_load_lds_dwordx4 v[2:3], off
	v_lshl_add_u64 v[2:3], v[4:5], 0, s[10:11]
	s_mov_b32 m0, s51
	s_addc_u32 s17, s45, 0
	global_load_lds_dwordx4 v[2:3], off
	s_add_i32 m0, s3, 0x1c000
	v_lshl_add_u64 v[2:3], s[16:17], 0, v[158:159]
	global_load_lds_dwordx4 v[2:3], off
	v_lshl_add_u64 v[2:3], s[16:17], 0, v[160:161]
	s_add_i32 m0, s3, 0x1e000
	s_mov_b64 s[16:17], 0x80080
	global_load_lds_dwordx4 v[2:3], off
	s_waitcnt vmcnt(8)
	s_barrier
	v_bfe_u32 v3, v1, 4, 2
	v_and_b32_e32 v2, 15, v1
	v_lshlrev_b32_e32 v4, 4, v3
	v_lshlrev_b32_e32 v1, 2, v1
	v_lshl_or_b32 v151, s0, 6, v2
	v_lshl_or_b32 v4, v2, 6, v4
	v_and_b32_e32 v1, 32, v1
	s_lshl_b32 s0, s0, 9
	v_bitop3_b32 v5, v4, s1, v1 bitop3:0xde
	v_bitop3_b32 v153, v4, s15, v1 bitop3:0xde
	s_cmpk_lt_u32 s14, 0x100
	v_lshlrev_b32_e32 v1, 2, v3
	s_cselect_b64 s[18:19], -1, 0
	v_lshl_or_b32 v155, s41, 5, v1
	s_add_i32 s1, 0, 0x20000
	v_lshlrev_b32_e32 v1, 15, v10
	v_add_u32_e32 v157, s1, v152
	v_lshl_add_u32 v183, v151, 3, s1
	s_add_i32 s1, s1, s0
	v_and_b32_e32 v1, 0xffff0000, v1
	v_lshl_add_u32 v184, v2, 3, s1
	v_lshl_add_u32 v1, v11, 12, v1
	v_and_b32_e32 v2, 1, v10
	v_lshl_or_b32 v1, v2, 6, v1
	v_lshl_add_u32 v2, v12, 1, v1
	v_lshlrev_b32_e32 v1, 15, v13
	v_cmp_eq_u32_e64 s[14:15], 0, v3
	v_mov_b32_e32 v3, v0
	v_and_b32_e32 v1, 0xffff0000, v1
	v_lshl_add_u64 v[162:163], v[2:3], 0, s[16:17]
	v_lshl_add_u32 v1, v14, 12, v1
	v_and_b32_e32 v2, 1, v13
	s_waitcnt vmcnt(6)
	v_lshl_or_b32 v1, v2, 6, v1
	v_lshl_add_u32 v2, v15, 1, v1
	s_ashr_i32 s52, s90, 31
	s_mov_b32 s53, s90
	v_readlane_b32 s54, v247, 54
	v_lshl_add_u64 v[164:165], v[2:3], 0, s[16:17]
	v_mov_b64_e32 v[166:167], 0x400
	v_mov_b64_e32 v[168:169], 0x3ff
	v_mov_b32_e32 v185, 0x358637bd
	s_add_i32 s55, 0, 0x10000
	s_add_i32 s60, 0, 0x14000
	v_add_u32_e32 v186, 0, v5
	s_mov_b32 s46, 0
	s_mov_b32 s61, 0
	s_barrier
	s_branch .LBB0_1067

; #define PG8_STAGE(bufoff, gbase, voff) do { _Pragma("unroll") for (int _i = 0; _i < 2; ++_i) \
;         __builtin_amdgcn_global_load_lds((const unsigned*)((const char*)(gbase) + (voff)[_i]), (PG8_LAS unsigned*)(lds + (bufoff) + ldsw + _i * 8192), 16, 0, 0); } while (0)
; #define PG8_WAIT_V(n) asm volatile("s_waitcnt vmcnt(" #n ")" ::: "memory")
; #define PG8_BAR __builtin_amdgcn_s_barrier()
; template <class Epi, class Sched>
; __device__ __forceinline__ void gemm_phase(PG8_LAS unsigned char* lds, const Gemm g, const Sched& S, const Epi& E) {
;     ...
;     const int aoff = lds_byte(wr * 64 + fr, fq * 8), boff = lds_byte(wc * 32 + fr, fq * 8);
;     ...
;     PG8_STAGE(PG8_SB(0, 0), cB, voffB); PG8_STAGE(PG8_SB(0, 1), cB + hstep, voffB); PG8_STAGE(PG8_SA(0, 0), cA, voffA); PG8_STAGE(PG8_SA(0, 1), cA + hstep, voffA);
;     if (wr == 1) PG8_BAR;
;     PG8_WAIT_V(2); PG8_BAR;
;     PG8_STAGE(PG8_SB(1, 0), cB + kstep, voffB); PG8_STAGE(PG8_SA(1, 0), cA + kstep, voffA); PG8_STAGE(PG8_SB(1, 1), cB + hstep + kstep, voffB);
;     PG8_WAIT_V(6); PG8_BAR;
.LBB0_1104:
	s_lshl_b32 s1, s1, 5
	s_mov_b64 s[8:9], 0x80
	s_and_b32 s1, s1, 0x60
	s_add_i32 m0, s3, 0x18000
	v_lshl_add_u64 v[6:7], v[6:7], 0, s[8:9]
	s_lshl_b32 s22, s4, 6
	s_lshl_b32 s4, s4, 13
	s_lshl_b32 s23, s1, 7
	global_load_lds_dwordx4 v[6:7], off
	v_lshl_add_u64 v[4:5], v[4:5], 0, s[8:9]
	s_add_i32 m0, s3, 0x1a000
	s_add_i32 s56, s3, 0x8000
	s_add_i32 s57, s3, 0xa000
	global_load_lds_dwordx4 v[4:5], off
	v_lshl_add_u64 v[0:1], v[0:1], 0, s[8:9]
	s_mov_b32 m0, s56
	s_add_u32 s16, s14, 0x80080
	global_load_lds_dwordx4 v[0:1], off
	v_lshl_add_u64 v[0:1], v[2:3], 0, s[8:9]
	s_mov_b32 m0, s57
	s_addc_u32 s17, s15, 0
	global_load_lds_dwordx4 v[0:1], off
	s_add_i32 m0, s3, 0x1c000
	v_lshl_add_u64 v[0:1], s[16:17], 0, v[130:131]
	global_load_lds_dwordx4 v[0:1], off
	v_lshl_add_u64 v[0:1], s[16:17], 0, v[128:129]
	s_add_i32 m0, s3, 0x1e000
	v_bfe_u32 v2, v8, 4, 2
	global_load_lds_dwordx4 v[0:1], off
	s_waitcnt vmcnt(8)
	s_barrier
	v_and_b32_e32 v0, 15, v8
	v_lshlrev_b32_e32 v1, 4, v2
	v_lshlrev_b32_e32 v3, 2, v8
	s_cmpk_lt_u32 s0, 0x100
	v_lshl_or_b32 v1, v0, 6, v1
	v_and_b32_e32 v3, 32, v3
	s_cselect_b64 s[16:17], -1, 0
	s_ashr_i32 s0, s22, 31
	v_bitop3_b32 v4, v1, s4, v3 bitop3:0xde
	v_bitop3_b32 v3, v1, s23, v3 bitop3:0xde
	s_waitcnt vmcnt(6)
	v_or_b32_e32 v0, s22, v0
	v_mov_b32_e32 v1, s0
	v_readlane_b32 s22, v246, 29
	s_add_i32 s62, 0, 0x10000
	s_add_i32 s64, 0, 0x14000
	v_lshlrev_b32_e32 v2, 2, v2
	v_lshlrev_b64 v[0:1], 13, v[0:1]
	v_readlane_b32 s23, v246, 30
	v_add_u32_e32 v136, s62, v3
	v_add_u32_e32 v137, s64, v3
	s_add_i32 s62, s62, s2
	s_add_i32 s64, s64, s2
	s_add_i32 s66, 0, 0x18000
	s_add_i32 s67, 0, 0x1c000
	v_lshl_add_u64 v[134:135], s[22:23], 0, v[0:1]
	v_add_u32_e32 v138, 0, v4
	s_lshl_b32 s4, s1, 2
	v_lshlrev_b32_e32 v132, 2, v2
	s_add_i32 s60, s3, 0xc000
	s_add_i32 s61, s3, 0xe000
	s_add_i32 s63, s62, 0x2000
	s_add_i32 s65, s64, 0x2000
	v_add_u32_e32 v139, s66, v3
	v_add_u32_e32 v140, s67, v3
	s_mov_b32 s68, s5
	s_barrier
	s_branch .LBB0_1107

; #define PG8_STAGE(bufoff, gbase, voff) do { _Pragma("unroll") for (int _i = 0; _i < 2; ++_i) \
;         __builtin_amdgcn_global_load_lds((const unsigned*)((const char*)(gbase) + (voff)[_i]), (PG8_LAS unsigned*)(lds + (bufoff) + ldsw + _i * 8192), 16, 0, 0); } while (0)
; #define PG8_WAIT_V(n) asm volatile("s_waitcnt vmcnt(" #n ")" ::: "memory")
; #define PG8_BAR __builtin_amdgcn_s_barrier()
; template <class Epi, class Sched>
; __device__ __forceinline__ void gemm_phase(PG8_LAS unsigned char* lds, const Gemm g, const Sched& S, const Epi& E) {
;     ...
;     const int aoff = lds_byte(wr * 64 + fr, fq * 8), boff = lds_byte(wc * 32 + fr, fq * 8);
;     ...
;     PG8_STAGE(PG8_SB(0, 0), cB, voffB); PG8_STAGE(PG8_SB(0, 1), cB + hstep, voffB); PG8_STAGE(PG8_SA(0, 0), cA, voffA); PG8_STAGE(PG8_SA(0, 1), cA + hstep, voffA);
;     if (wr == 1) PG8_BAR;
;     PG8_WAIT_V(2); PG8_BAR;
;     PG8_STAGE(PG8_SB(1, 0), cB + kstep, voffB); PG8_STAGE(PG8_SA(1, 0), cA + kstep, voffA); PG8_STAGE(PG8_SB(1, 1), cB + hstep + kstep, voffB);
;     PG8_WAIT_V(6); PG8_BAR;
.LBB0_1240:
	s_lshl_b32 s6, s6, 5
	s_and_b32 s14, s6, 0x60
	s_mov_b64 s[6:7], 0x80
	s_add_i32 m0, s3, 0x18000
	v_lshl_add_u64 v[6:7], v[6:7], 0, s[6:7]
	s_lshl_b32 s11, s10, 13
	s_lshl_b32 s15, s14, 7
	global_load_lds_dwordx4 v[6:7], off
	v_lshl_add_u64 v[4:5], v[4:5], 0, s[6:7]
	s_add_i32 m0, s3, 0x1a000
	s_add_i32 s40, s3, 0x8000
	s_add_i32 s41, s3, 0xa000
	global_load_lds_dwordx4 v[4:5], off
	v_lshl_add_u64 v[0:1], v[0:1], 0, s[6:7]
	s_mov_b32 m0, s40
	s_add_u32 s12, s34, 0x80080
	global_load_lds_dwordx4 v[0:1], off
	v_lshl_add_u64 v[0:1], v[2:3], 0, s[6:7]
	s_mov_b32 m0, s41
	s_addc_u32 s13, s35, 0
	global_load_lds_dwordx4 v[0:1], off
	s_add_i32 m0, s3, 0x1c000
	v_lshl_add_u64 v[0:1], s[12:13], 0, v[130:131]
	global_load_lds_dwordx4 v[0:1], off
	v_lshl_add_u64 v[0:1], s[12:13], 0, v[134:135]
	s_add_i32 m0, s3, 0x1e000
	s_cmpk_lt_u32 s9, 0x100
	global_load_lds_dwordx4 v[0:1], off
	s_waitcnt vmcnt(8)
	s_barrier
	v_lshrrev_b32_e32 v1, 1, v8
	v_and_b32_e32 v1, 24, v1
	v_and_b32_e32 v0, 15, v8
	v_lshlrev_b32_e32 v2, 1, v1
	v_lshl_or_b32 v146, s10, 6, v0
	v_lshl_or_b32 v0, v0, 6, v2
	v_lshlrev_b32_e32 v2, 2, v8
	v_and_b32_e32 v2, 32, v2
	v_bitop3_b32 v3, v0, s11, v2 bitop3:0xde
	v_bitop3_b32 v147, v0, s15, v2 bitop3:0xde
	v_lshlrev_b32_e32 v0, 15, v9
	v_and_b32_e32 v0, 0xffff0000, v0
	v_or_b32_e32 v151, s14, v1
	v_lshl_add_u32 v0, v10, 12, v0
	v_and_b32_e32 v1, 1, v9
	v_lshl_or_b32 v0, v1, 6, v0
	v_lshl_add_u32 v136, v11, 1, v0
	v_lshlrev_b32_e32 v0, 15, v12
	v_and_b32_e32 v0, 0xffff0000, v0
	s_waitcnt vmcnt(6)
	v_lshl_add_u32 v0, v13, 12, v0
	v_and_b32_e32 v1, 1, v12
	s_sext_i32_i16 s48, s8
	s_cselect_b64 s[8:9], -1, 0
	v_lshl_or_b32 v0, v1, 6, v0
	s_add_i32 s45, 0, 0x10000
	s_add_i32 s46, 0, 0x14000
	s_ashr_i32 s42, s90, 31
	s_mov_b32 s43, s90
	v_readlane_b32 s44, v247, 54
	v_mov_b32_e32 v137, v131
	v_lshl_add_u32 v138, v14, 1, v0
	v_mov_b32_e32 v139, v131
	v_mov_b64_e32 v[140:141], 0x15ab
	v_mov_b64_e32 v[142:143], 0x15aa
	v_add_u32_e32 v152, s45, v147
	v_add_u32_e32 v153, s46, v147
	v_add_u32_e32 v155, 0, v3
	v_mov_b32_e32 v156, 0x358637bd
	s_movk_i32 s47, 0x2b00
	s_barrier
	s_branch .LBB0_1243

; #define PG8_STAGE(bufoff, gbase, voff) do { _Pragma("unroll") for (int _i = 0; _i < 2; ++_i) \
;         __builtin_amdgcn_global_load_lds((const unsigned*)((const char*)(gbase) + (voff)[_i]), (PG8_LAS unsigned*)(lds + (bufoff) + ldsw + _i * 8192), 16, 0, 0); } while (0)
; #define PG8_WAIT_V(n) asm volatile("s_waitcnt vmcnt(" #n ")" ::: "memory")
; #define PG8_BAR __builtin_amdgcn_s_barrier()
; template <class Epi, class Sched>
; __device__ __forceinline__ void gemm_phase(PG8_LAS unsigned char* lds, const Gemm g, const Sched& S, const Epi& E) {
;     ...
;     const int aoff = lds_byte(wr * 64 + fr, fq * 8), boff = lds_byte(wc * 32 + fr, fq * 8);
;     ...
;     PG8_STAGE(PG8_SB(0, 0), cB, voffB); PG8_STAGE(PG8_SB(0, 1), cB + hstep, voffB); PG8_STAGE(PG8_SA(0, 0), cA, voffA); PG8_STAGE(PG8_SA(0, 1), cA + hstep, voffA);
;     if (wr == 1) PG8_BAR;
;     PG8_WAIT_V(2); PG8_BAR;
;     PG8_STAGE(PG8_SB(1, 0), cB + kstep, voffB); PG8_STAGE(PG8_SA(1, 0), cA + kstep, voffA); PG8_STAGE(PG8_SB(1, 1), cB + hstep + kstep, voffB);
;     PG8_WAIT_V(6); PG8_BAR;
.LBB0_1316:
	s_lshl_b32 s8, s8, 5
	s_and_b32 s14, s8, 0x60
	s_mov_b64 s[8:9], 0x80
	s_add_i32 m0, s3, 0x18000
	v_lshl_add_u64 v[6:7], v[6:7], 0, s[8:9]
	s_lshl_b32 s12, s1, 13
	s_lshl_b32 s13, s14, 7
	global_load_lds_dwordx4 v[6:7], off
	v_lshl_add_u64 v[4:5], v[4:5], 0, s[8:9]
	s_add_i32 m0, s3, 0x1a000
	s_add_i32 s43, s3, 0x8000
	s_add_i32 s44, s3, 0xa000
	global_load_lds_dwordx4 v[4:5], off
	v_lshl_add_u64 v[0:1], v[0:1], 0, s[8:9]
	s_mov_b32 m0, s43
	s_add_u32 s10, s34, 0x158080
	global_load_lds_dwordx4 v[0:1], off
	v_lshl_add_u64 v[0:1], v[2:3], 0, s[8:9]
	s_mov_b32 m0, s44
	s_addc_u32 s11, s35, 0
	global_load_lds_dwordx4 v[0:1], off
	s_add_i32 m0, s3, 0x1c000
	v_lshl_add_u64 v[0:1], s[10:11], 0, v[128:129]
	global_load_lds_dwordx4 v[0:1], off
	v_lshl_add_u64 v[0:1], s[10:11], 0, v[130:131]
	s_add_i32 m0, s3, 0x1e000
	s_sext_i32_i8 s53, s5
	global_load_lds_dwordx4 v[0:1], off
	s_waitcnt vmcnt(8)
	s_barrier
	v_bfe_u32 v1, v8, 4, 2
	v_and_b32_e32 v0, 15, v8
	v_lshlrev_b32_e32 v2, 4, v1
	v_lshl_or_b32 v146, s1, 6, v0
	v_lshl_or_b32 v0, v0, 6, v2
	v_lshlrev_b32_e32 v2, 2, v8
	v_and_b32_e32 v2, 32, v2
	v_bitop3_b32 v3, v0, s12, v2 bitop3:0xde
	v_bitop3_b32 v147, v0, s13, v2 bitop3:0xde
	v_lshl_or_b32 v151, v1, 2, s14
	v_lshrrev_b32_e32 v1, 1, v9
	v_mul_lo_u32 v0, v11, s0
	s_mov_b32 s1, 0x15800
	s_cmpk_lt_u32 s4, 0x100
	v_mad_u64_u32 v[0:1], s[4:5], v1, s1, v[0:1]
	v_or_b32_e32 v0, v0, v10
	s_mov_b64 s[12:13], 0x158080
	v_add_lshl_u32 v0, v0, v12, 1
	v_mov_b32_e32 v1, v129
	v_lshl_add_u64 v[132:133], v[0:1], 0, s[12:13]
	v_lshrrev_b32_e32 v1, 1, v13
	v_mul_lo_u32 v0, v14, s0
	v_mad_u64_u32 v[0:1], s[0:1], v1, s1, v[0:1]
	s_waitcnt vmcnt(6)
	v_or_b32_e32 v0, v0, v15
	s_cselect_b64 s[10:11], -1, 0
	v_add_lshl_u32 v0, v0, v16, 1
	v_mov_b32_e32 v1, v129
	s_add_i32 s48, 0, 0x10000
	s_add_i32 s49, 0, 0x14000
	s_ashr_i32 s45, s90, 31
	s_mov_b32 s46, s90
	v_readlane_b32 s47, v247, 54
	v_lshl_add_u64 v[134:135], v[0:1], 0, s[12:13]
	v_mov_b64_e32 v[136:137], 0x400
	v_mov_b64_e32 v[138:139], 0x3ff
	v_add_u32_e32 v152, s48, v147
	v_add_u32_e32 v153, s49, v147
	v_add_u32_e32 v155, 0, v3
	s_mov_b64 s[12:13], 0x100000
	s_mov_b64 s[14:15], 0x120000
	s_mov_b64 s[16:17], 0x140000
	s_mov_b64 s[18:19], 0x160000
	s_barrier
	s_branch .LBB0_1319

; #define PG8_STAGE(bufoff, gbase, voff) do { _Pragma("unroll") for (int _i = 0; _i < 2; ++_i) \
;         __builtin_amdgcn_global_load_lds((const unsigned*)((const char*)(gbase) + (voff)[_i]), (PG8_LAS unsigned*)(lds + (bufoff) + ldsw + _i * 8192), 16, 0, 0); } while (0)
; #define PG8_WAIT_V(n) asm volatile("s_waitcnt vmcnt(" #n ")" ::: "memory")
; #define PG8_BAR __builtin_amdgcn_s_barrier()
; template <class Epi, class Sched>
; __device__ __forceinline__ void gemm_phase(PG8_LAS unsigned char* lds, const Gemm g, const Sched& S, const Epi& E) {
;     ...
;     const int aoff = lds_byte(wr * 64 + fr, fq * 8), boff = lds_byte(wc * 32 + fr, fq * 8);
;     ...
;     PG8_STAGE(PG8_SB(0, 0), cB, voffB); PG8_STAGE(PG8_SB(0, 1), cB + hstep, voffB); PG8_STAGE(PG8_SA(0, 0), cA, voffA); PG8_STAGE(PG8_SA(0, 1), cA + hstep, voffA);
;     if (wr == 1) PG8_BAR;
;     PG8_WAIT_V(2); PG8_BAR;
;     PG8_STAGE(PG8_SB(1, 0), cB + kstep, voffB); PG8_STAGE(PG8_SA(1, 0), cA + kstep, voffA); PG8_STAGE(PG8_SB(1, 1), cB + hstep + kstep, voffB);
;     PG8_WAIT_V(6); PG8_BAR;
.LBB0_1340:
	s_cmpk_gt_i32 s66, 0x9f
	s_cselect_b32 s54, 6, 4
	s_lshl_b32 s16, s8, 6
	s_lshl_b32 s14, s8, 13
	s_lshl_b32 s4, s4, 5
	s_mov_b64 s[8:9], 0x80
	s_and_b32 s4, s4, 0x60
	s_add_i32 m0, s3, 0x18000
	v_lshl_add_u64 v[6:7], v[6:7], 0, s[8:9]
	s_lshl_b32 s15, s4, 7
	global_load_lds_dwordx4 v[6:7], off
	v_lshl_add_u64 v[4:5], v[4:5], 0, s[8:9]
	s_add_i32 m0, s3, 0x1a000
	s_add_i32 s42, s3, 0x8000
	s_add_i32 s43, s3, 0xa000
	global_load_lds_dwordx4 v[4:5], off
	v_lshl_add_u64 v[0:1], v[0:1], 0, s[8:9]
	s_mov_b32 m0, s42
	s_add_u32 s12, s22, 0x158080
	global_load_lds_dwordx4 v[0:1], off
	v_lshl_add_u64 v[0:1], v[2:3], 0, s[8:9]
	s_mov_b32 m0, s43
	s_addc_u32 s13, s23, 0
	global_load_lds_dwordx4 v[0:1], off
	s_add_i32 m0, s3, 0x1c000
	v_lshl_add_u64 v[0:1], s[12:13], 0, v[130:131]
	global_load_lds_dwordx4 v[0:1], off
	v_lshl_add_u64 v[0:1], s[12:13], 0, v[128:129]
	s_add_i32 m0, s3, 0x1e000
	v_bfe_u32 v2, v148, 4, 2
	global_load_lds_dwordx4 v[0:1], off
	s_waitcnt vmcnt(8)
	s_barrier
	v_and_b32_e32 v0, 15, v148
	v_lshlrev_b32_e32 v1, 4, v2
	v_lshlrev_b32_e32 v3, 2, v148
	s_cmpk_lt_u32 s0, 0x100
	v_lshl_or_b32 v1, v0, 6, v1
	v_and_b32_e32 v3, 32, v3
	s_cselect_b64 s[12:13], -1, 0
	s_ashr_i32 s0, s16, 31
	v_bitop3_b32 v4, v1, s14, v3 bitop3:0xde
	v_bitop3_b32 v140, v1, s15, v3 bitop3:0xde
	v_or_b32_e32 v0, s16, v0
	v_mov_b32_e32 v1, s0
	v_readlane_b32 s16, v246, 29
	v_lshlrev_b64 v[0:1], 13, v[0:1]
	v_readlane_b32 s17, v246, 30
	s_mov_b32 s0, 0x15800
	s_mov_b64 s[14:15], 0x158080
	v_lshl_add_u64 v[134:135], s[16:17], 0, v[0:1]
	v_lshrrev_b32_e32 v1, 1, v13
	v_mul_lo_u32 v0, v12, s1
	v_mad_u64_u32 v[0:1], s[16:17], v1, s0, v[0:1]
	v_or_b32_e32 v0, v0, v14
	v_add_lshl_u32 v132, v0, v15, 1
	v_lshrrev_b32_e32 v1, 1, v8
	v_mul_lo_u32 v0, v9, s1
	v_mad_u64_u32 v[0:1], s[0:1], v1, s0, v[0:1]
	s_waitcnt vmcnt(6)
	v_or_b32_e32 v0, v0, v10
	v_lshlrev_b32_e32 v2, 2, v2
	v_lshl_add_u64 v[136:137], v[132:133], 0, s[14:15]
	v_add_lshl_u32 v132, v0, v11, 1
	s_add_i32 s44, 0, 0x10000
	s_add_i32 s45, 0, 0x14000
	v_lshl_add_u64 v[138:139], v[132:133], 0, s[14:15]
	v_add_u32_e32 v141, s44, v140
	v_add_u32_e32 v142, s45, v140
	v_add_u32_e32 v143, 0, v4
	s_lshl_b32 s4, s4, 2
	v_lshlrev_b32_e32 v132, 2, v2
	s_mov_b32 s46, 0x20000
	s_mov_b32 s47, 0x40000
	s_mov_b32 s48, 0x60000
	s_mov_b32 s49, 0x100000
	s_mov_b32 s50, 0x120000
	s_mov_b32 s51, s5
	s_barrier
	s_branch .LBB0_1343
